# speedup vs baseline: 1.0896x; 1.0198x over previous
; #define RUNPH(n) { run_phase(p, (n), smem); grid.sync(); }
; __global__ void __launch_bounds__(256, 2) mega(Params p) {
;   extern __shared__ __attribute__((aligned(16))) char smem[];
;   cg::grid_group grid = cg::this_grid();
;   RUNPH(0) RUNPH(1) RUNPH(2) RUNPH(3) RUNPH(4) RUNPH(5) RUNPH(6) RUNPH(7) RUNPH(8)
;   RUNPH(18) RUNPH(19) RUNPH(9)
;   RUNPH(10) RUNPH(11) RUNPH(12) RUNPH(13) RUNPH(14) RUNPH(15) RUNPH(16)
.LBB0_169:
	s_waitcnt vmcnt(0)
	s_barrier
	s_mov_b64 s[4:5], exec
	v_readlane_b32 s0, v225, 14
	v_readlane_b32 s1, v225, 15
	s_and_b64 s[0:1], s[4:5], s[0:1]
	s_mov_b64 exec, s[0:1]
	s_cbranch_execz .LBB0_179
	s_getreg_b32 s0, hwreg(HW_REG_XCC_ID, 0, 4)
	s_and_b32 s0, s0, 15
	s_lshl_b32 s0, 1, s0
	s_and_b32 s1, s98, 7
	s_lshl_b32 s1, s1, 8
	s_mov_b32 s100, 0
	v_mov_b32_e32 v0, s1
	v_mov_b32_e32 v1, s0
	s_add_u32 s6, s30, 0x3eb3a000
	s_addc_u32 s7, s31, 0
	global_atomic_or v0, v1, s[6:7]
	buffer_wbl2 sc1
	s_waitcnt vmcnt(0)
	s_and_b32 s0, s98, 7
	s_sub_u32 s1, s99, s0
	s_add_u32 s1, s1, 7
	s_lshr_b32 s1, s1, 3
	s_mul_i32 s1, s1, 1
	s_lshl_b32 s0, s0, 8
	v_mov_b32_e32 v2, s0
	v_mov_b32_e32 v0, 0
	v_mov_b32_e32 v1, 1
	s_add_u32 s6, s30, 0x3eb38000
	s_addc_u32 s7, s31, 0
	s_mov_b32 s8, 0
	global_atomic_add v3, v2, v1, s[6:7] sc0
	s_waitcnt vmcnt(0)
	v_readfirstlane_b32 s0, v3
	s_add_u32 s0, s0, 1
	s_cmp_eq_u32 s0, s1
	s_cbranch_scc0 .Lgb1_pollg
	s_add_u32 s6, s6, 0x1000
	s_addc_u32 s7, s7, 0
	global_atomic_add v3, v0, v1, s[6:7] sc0
	s_min_u32 s1, s99, 8
	s_mul_i32 s1, s1, 1
	s_waitcnt vmcnt(0)
	v_readfirstlane_b32 s0, v3
	s_add_u32 s0, s0, 1
	s_cmp_eq_u32 s0, s1
	s_cbranch_scc0 .Lgb1_pollt
	global_atomic_add v0, v1, s[6:7] offset:256
	s_branch .Lgb1_relg

; #define RUNPH(n) { run_phase(p, (n), smem); grid.sync(); }
; __global__ void __launch_bounds__(256, 2) mega(Params p) {
;   extern __shared__ __attribute__((aligned(16))) char smem[];
;   cg::grid_group grid = cg::this_grid();
;   RUNPH(0) RUNPH(1) RUNPH(2) RUNPH(3) RUNPH(4) RUNPH(5) RUNPH(6) RUNPH(7) RUNPH(8)
;   RUNPH(18) RUNPH(19) RUNPH(9)
;   RUNPH(10) RUNPH(11) RUNPH(12) RUNPH(13) RUNPH(14) RUNPH(15) RUNPH(16)
.Lgb1_done:
	s_add_u32 s6, s30, 0x3eb3a000
	s_addc_u32 s7, s31, 0
	s_and_b32 s1, s98, 7
	s_lshl_b32 s1, s1, 8
	v_mov_b32_e32 v0, s1
	global_load_dword v3, v0, s[6:7] sc1
	s_waitcnt vmcnt(0)
	v_readfirstlane_b32 s0, v3
	s_bcnt1_i32_b32 s0, s0
	s_cmp_eq_u32 s0, 1
	s_cselect_b32 s100, 1, 0
	buffer_inv sc1
	s_waitcnt vmcnt(0)

; #define RUNPH(n) { run_phase(p, (n), smem); grid.sync(); }
; __global__ void __launch_bounds__(256, 2) mega(Params p) {
;   extern __shared__ __attribute__((aligned(16))) char smem[];
;   cg::grid_group grid = cg::this_grid();
;   RUNPH(0) RUNPH(1) RUNPH(2) RUNPH(3) RUNPH(4) RUNPH(5) RUNPH(6) RUNPH(7) RUNPH(8)
;   RUNPH(18) RUNPH(19) RUNPH(9)
;   RUNPH(10) RUNPH(11) RUNPH(12) RUNPH(13) RUNPH(14) RUNPH(15) RUNPH(16)
.LBB0_182:
	s_or_b64 exec, exec, s[18:19]
	s_waitcnt vmcnt(0)
	s_barrier
	s_mov_b64 s[4:5], exec
	v_readlane_b32 s0, v225, 14
	v_readlane_b32 s1, v225, 15
	s_and_b64 s[0:1], s[4:5], s[0:1]
	s_mov_b64 exec, s[0:1]
	s_cbranch_execz .LBB0_192
	s_cmp_eq_u32 s100, 1
	s_cbranch_scc1 .Lgb2_nowb
	buffer_wbl2 sc1
	s_waitcnt vmcnt(0)
.Lgb2_nowb:
	s_and_b32 s0, s98, 7
	s_sub_u32 s1, s99, s0
	s_add_u32 s1, s1, 7
	s_lshr_b32 s1, s1, 3
	s_mul_i32 s1, s1, 2
	s_lshl_b32 s0, s0, 8
	v_mov_b32_e32 v2, s0
	v_mov_b32_e32 v0, 0
	v_mov_b32_e32 v1, 1
	s_add_u32 s6, s30, 0x3eb38000
	s_addc_u32 s7, s31, 0
	s_mov_b32 s8, 0
	global_atomic_add v3, v2, v1, s[6:7] sc0
	s_waitcnt vmcnt(0)
	v_readfirstlane_b32 s0, v3
	s_add_u32 s0, s0, 1
	s_cmp_eq_u32 s0, s1
	s_cbranch_scc0 .Lgb2_pollg
	buffer_wbl2 sc1
	s_waitcnt vmcnt(0)
	s_add_u32 s6, s6, 0x1000
	s_addc_u32 s7, s7, 0
	global_atomic_add v3, v0, v1, s[6:7] sc0
	s_min_u32 s1, s99, 8
	s_mul_i32 s1, s1, 2
	s_waitcnt vmcnt(0)
	v_readfirstlane_b32 s0, v3
	s_add_u32 s0, s0, 1
	s_cmp_eq_u32 s0, s1
	s_cbranch_scc0 .Lgb2_pollt
	global_atomic_add v0, v1, s[6:7] offset:256
	s_branch .Lgb2_relg

; #define RUNPH(n) { run_phase(p, (n), smem); grid.sync(); }
; __global__ void __launch_bounds__(256, 2) mega(Params p) {
;   extern __shared__ __attribute__((aligned(16))) char smem[];
;   cg::grid_group grid = cg::this_grid();
;   RUNPH(0) RUNPH(1) RUNPH(2) RUNPH(3) RUNPH(4) RUNPH(5) RUNPH(6) RUNPH(7) RUNPH(8)
;   RUNPH(18) RUNPH(19) RUNPH(9)
;   RUNPH(10) RUNPH(11) RUNPH(12) RUNPH(13) RUNPH(14) RUNPH(15) RUNPH(16)
.LBB0_205:
	s_waitcnt vmcnt(0)
	s_barrier
	s_mov_b64 s[4:5], exec
	v_readlane_b32 s0, v225, 14
	v_readlane_b32 s1, v225, 15
	s_and_b64 s[0:1], s[4:5], s[0:1]
	s_mov_b64 exec, s[0:1]
	s_cbranch_execz .LBB0_215
	s_cmp_eq_u32 s100, 1
	s_cbranch_scc1 .Lgb3_nowb
	buffer_wbl2 sc1
	s_waitcnt vmcnt(0)
.Lgb3_nowb:
	s_and_b32 s0, s98, 7
	s_sub_u32 s1, s99, s0
	s_add_u32 s1, s1, 7
	s_lshr_b32 s1, s1, 3
	s_mul_i32 s1, s1, 3
	s_lshl_b32 s0, s0, 8
	v_mov_b32_e32 v2, s0
	v_mov_b32_e32 v0, 0
	v_mov_b32_e32 v1, 1
	s_add_u32 s6, s30, 0x3eb38000
	s_addc_u32 s7, s31, 0
	s_mov_b32 s8, 0
	global_atomic_add v3, v2, v1, s[6:7] sc0
	s_waitcnt vmcnt(0)
	v_readfirstlane_b32 s0, v3
	s_add_u32 s0, s0, 1
	s_cmp_eq_u32 s0, s1
	s_cbranch_scc0 .Lgb3_pollg
	buffer_wbl2 sc1
	s_waitcnt vmcnt(0)
	s_add_u32 s6, s6, 0x1000
	s_addc_u32 s7, s7, 0
	global_atomic_add v3, v0, v1, s[6:7] sc0
	s_min_u32 s1, s99, 8
	s_mul_i32 s1, s1, 3
	s_waitcnt vmcnt(0)
	v_readfirstlane_b32 s0, v3
	s_add_u32 s0, s0, 1
	s_cmp_eq_u32 s0, s1
	s_cbranch_scc0 .Lgb3_pollt
	global_atomic_add v0, v1, s[6:7] offset:256
	s_branch .Lgb3_relg

; #define RUNPH(n) { run_phase(p, (n), smem); grid.sync(); }
; __global__ void __launch_bounds__(256, 2) mega(Params p) {
;   extern __shared__ __attribute__((aligned(16))) char smem[];
;   cg::grid_group grid = cg::this_grid();
;   RUNPH(0) RUNPH(1) RUNPH(2) RUNPH(3) RUNPH(4) RUNPH(5) RUNPH(6) RUNPH(7) RUNPH(8)
;   RUNPH(18) RUNPH(19) RUNPH(9)
;   RUNPH(10) RUNPH(11) RUNPH(12) RUNPH(13) RUNPH(14) RUNPH(15) RUNPH(16)
.Lgb4_nowb:
	s_and_b32 s0, s98, 7
	s_sub_u32 s1, s99, s0
	s_add_u32 s1, s1, 7
	s_lshr_b32 s1, s1, 3
	s_mul_i32 s1, s1, 4
	s_lshl_b32 s0, s0, 8
	v_mov_b32_e32 v2, s0
	v_mov_b32_e32 v0, 0
	v_mov_b32_e32 v1, 1
	s_add_u32 s6, s30, 0x3eb38000
	s_addc_u32 s7, s31, 0
	s_mov_b32 s8, 0
	global_atomic_add v3, v2, v1, s[6:7] sc0
	s_waitcnt vmcnt(0)
	v_readfirstlane_b32 s0, v3
	s_add_u32 s0, s0, 1
	s_cmp_eq_u32 s0, s1
	s_cbranch_scc0 .Lgb4_pollg
	buffer_wbl2 sc1
	s_waitcnt vmcnt(0)
	s_add_u32 s6, s6, 0x1000
	s_addc_u32 s7, s7, 0
	global_atomic_add v3, v0, v1, s[6:7] sc0
	s_min_u32 s1, s99, 8
	s_mul_i32 s1, s1, 4
	s_waitcnt vmcnt(0)
	v_readfirstlane_b32 s0, v3
	s_add_u32 s0, s0, 1
	s_cmp_eq_u32 s0, s1
	s_cbranch_scc0 .Lgb4_pollt
	global_atomic_add v0, v1, s[6:7] offset:256
	s_branch .Lgb4_relg

; #define RUNPH(n) { run_phase(p, (n), smem); grid.sync(); }
; __global__ void __launch_bounds__(256, 2) mega(Params p) {
;   extern __shared__ __attribute__((aligned(16))) char smem[];
;   cg::grid_group grid = cg::this_grid();
;   RUNPH(0) RUNPH(1) RUNPH(2) RUNPH(3) RUNPH(4) RUNPH(5) RUNPH(6) RUNPH(7) RUNPH(8)
;   RUNPH(18) RUNPH(19) RUNPH(9)
;   RUNPH(10) RUNPH(11) RUNPH(12) RUNPH(13) RUNPH(14) RUNPH(15) RUNPH(16)
.Lgb5_nowb:
	s_and_b32 s0, s98, 7
	s_sub_u32 s1, s99, s0
	s_add_u32 s1, s1, 7
	s_lshr_b32 s1, s1, 3
	s_mul_i32 s1, s1, 5
	s_lshl_b32 s0, s0, 8
	v_mov_b32_e32 v2, s0
	v_mov_b32_e32 v0, 0
	v_mov_b32_e32 v1, 1
	s_add_u32 s6, s30, 0x3eb38000
	s_addc_u32 s7, s31, 0
	s_mov_b32 s8, 0
	global_atomic_add v3, v2, v1, s[6:7] sc0
	s_waitcnt vmcnt(0)
	v_readfirstlane_b32 s0, v3
	s_add_u32 s0, s0, 1
	s_cmp_eq_u32 s0, s1
	s_cbranch_scc0 .Lgb5_pollg
	buffer_wbl2 sc1
	s_waitcnt vmcnt(0)
	s_add_u32 s6, s6, 0x1000
	s_addc_u32 s7, s7, 0
	global_atomic_add v3, v0, v1, s[6:7] sc0
	s_min_u32 s1, s99, 8
	s_mul_i32 s1, s1, 5
	s_waitcnt vmcnt(0)
	v_readfirstlane_b32 s0, v3
	s_add_u32 s0, s0, 1
	s_cmp_eq_u32 s0, s1
	s_cbranch_scc0 .Lgb5_pollt
	global_atomic_add v0, v1, s[6:7] offset:256
	s_branch .Lgb5_relg

; #define RUNPH(n) { run_phase(p, (n), smem); grid.sync(); }
; __global__ void __launch_bounds__(256, 2) mega(Params p) {
;   extern __shared__ __attribute__((aligned(16))) char smem[];
;   cg::grid_group grid = cg::this_grid();
;   RUNPH(0) RUNPH(1) RUNPH(2) RUNPH(3) RUNPH(4) RUNPH(5) RUNPH(6) RUNPH(7) RUNPH(8)
;   RUNPH(18) RUNPH(19) RUNPH(9)
;   RUNPH(10) RUNPH(11) RUNPH(12) RUNPH(13) RUNPH(14) RUNPH(15) RUNPH(16)
.LBB0_390:
	s_waitcnt lgkmcnt(0)
	s_waitcnt vmcnt(0)
	s_barrier
	s_mov_b64 s[4:5], exec
	v_readlane_b32 s0, v225, 14
	v_readlane_b32 s1, v225, 15
	s_and_b64 s[0:1], s[4:5], s[0:1]
	s_mov_b64 exec, s[0:1]
	s_cbranch_execz .LBB0_400
	s_cmp_eq_u32 s100, 1
	s_cbranch_scc1 .Lgb6_nowb
	buffer_wbl2 sc1
	s_waitcnt vmcnt(0)
.Lgb6_nowb:
	s_and_b32 s0, s98, 7
	s_sub_u32 s1, s99, s0
	s_add_u32 s1, s1, 7
	s_lshr_b32 s1, s1, 3
	s_mul_i32 s1, s1, 6
	s_lshl_b32 s0, s0, 8
	v_mov_b32_e32 v2, s0
	v_mov_b32_e32 v0, 0
	v_mov_b32_e32 v1, 1
	s_add_u32 s6, s30, 0x3eb38000
	s_addc_u32 s7, s31, 0
	s_mov_b32 s8, 0
	global_atomic_add v3, v2, v1, s[6:7] sc0
	s_waitcnt vmcnt(0)
	v_readfirstlane_b32 s0, v3
	s_add_u32 s0, s0, 1
	s_cmp_eq_u32 s0, s1
	s_cbranch_scc0 .Lgb6_pollg
	buffer_wbl2 sc1
	s_waitcnt vmcnt(0)
	s_add_u32 s6, s6, 0x1000
	s_addc_u32 s7, s7, 0
	global_atomic_add v3, v0, v1, s[6:7] sc0
	s_min_u32 s1, s99, 8
	s_mul_i32 s1, s1, 6
	s_waitcnt vmcnt(0)
	v_readfirstlane_b32 s0, v3
	s_add_u32 s0, s0, 1
	s_cmp_eq_u32 s0, s1
	s_cbranch_scc0 .Lgb6_pollt
	global_atomic_add v0, v1, s[6:7] offset:256
	s_branch .Lgb6_relg

; #define RUNPH(n) { run_phase(p, (n), smem); grid.sync(); }
; __global__ void __launch_bounds__(256, 2) mega(Params p) {
;   extern __shared__ __attribute__((aligned(16))) char smem[];
;   cg::grid_group grid = cg::this_grid();
;   RUNPH(0) RUNPH(1) RUNPH(2) RUNPH(3) RUNPH(4) RUNPH(5) RUNPH(6) RUNPH(7) RUNPH(8)
;   RUNPH(18) RUNPH(19) RUNPH(9)
;   RUNPH(10) RUNPH(11) RUNPH(12) RUNPH(13) RUNPH(14) RUNPH(15) RUNPH(16)
.LBB0_403:
	s_waitcnt vmcnt(0)
	s_barrier
	s_mov_b64 s[4:5], exec
	v_readlane_b32 s2, v225, 14
	v_readlane_b32 s3, v225, 15
	s_and_b64 s[2:3], s[4:5], s[2:3]
	v_readlane_b32 s34, v225, 2
	v_readlane_b32 s35, v225, 3
	s_mov_b64 exec, s[2:3]
	s_cbranch_execz .LBB0_413
	s_cmp_eq_u32 s100, 1
	s_cbranch_scc1 .Lgb7_nowb
	buffer_wbl2 sc1
	s_waitcnt vmcnt(0)
.Lgb7_nowb:
	s_and_b32 s2, s98, 7
	s_sub_u32 s3, s99, s2
	s_add_u32 s3, s3, 7
	s_lshr_b32 s3, s3, 3
	s_mul_i32 s3, s3, 7
	s_lshl_b32 s2, s2, 8
	v_mov_b32_e32 v2, s2
	v_mov_b32_e32 v0, 0
	v_mov_b32_e32 v1, 1
	s_add_u32 s6, s30, 0x3eb38000
	s_addc_u32 s7, s31, 0
	s_mov_b32 s8, 0
	global_atomic_add v3, v2, v1, s[6:7] sc0
	s_waitcnt vmcnt(0)
	v_readfirstlane_b32 s2, v3
	s_add_u32 s2, s2, 1
	s_cmp_eq_u32 s2, s3
	s_cbranch_scc0 .Lgb7_pollg
	buffer_wbl2 sc1
	s_waitcnt vmcnt(0)
	s_add_u32 s6, s6, 0x1000
	s_addc_u32 s7, s7, 0
	global_atomic_add v3, v0, v1, s[6:7] sc0
	s_min_u32 s3, s99, 8
	s_mul_i32 s3, s3, 7
	s_waitcnt vmcnt(0)
	v_readfirstlane_b32 s2, v3
	s_add_u32 s2, s2, 1
	s_cmp_eq_u32 s2, s3
	s_cbranch_scc0 .Lgb7_pollt
	global_atomic_add v0, v1, s[6:7] offset:256
	s_branch .Lgb7_relg

; #define RUNPH(n) { run_phase(p, (n), smem); grid.sync(); }
; __global__ void __launch_bounds__(256, 2) mega(Params p) {
;   extern __shared__ __attribute__((aligned(16))) char smem[];
;   cg::grid_group grid = cg::this_grid();
;   RUNPH(0) RUNPH(1) RUNPH(2) RUNPH(3) RUNPH(4) RUNPH(5) RUNPH(6) RUNPH(7) RUNPH(8)
;   RUNPH(18) RUNPH(19) RUNPH(9)
;   RUNPH(10) RUNPH(11) RUNPH(12) RUNPH(13) RUNPH(14) RUNPH(15) RUNPH(16)
.LBB0_451:
	s_waitcnt vmcnt(0)
	s_barrier
	s_mov_b64 s[6:7], exec
	v_readlane_b32 s0, v225, 14
	v_readlane_b32 s1, v225, 15
	s_and_b64 s[0:1], s[6:7], s[0:1]
	s_mov_b64 exec, s[0:1]
	s_cbranch_execz .LBB0_461
	s_cmp_eq_u32 s100, 1
	s_cbranch_scc1 .Lgb8_nowb
	buffer_wbl2 sc1
	s_waitcnt vmcnt(0)
.Lgb8_nowb:
	s_and_b32 s0, s98, 7
	s_sub_u32 s1, s99, s0
	s_add_u32 s1, s1, 7
	s_lshr_b32 s1, s1, 3
	s_mul_i32 s1, s1, 8
	s_lshl_b32 s0, s0, 8
	v_mov_b32_e32 v2, s0
	v_mov_b32_e32 v0, 0
	v_mov_b32_e32 v1, 1
	s_add_u32 s8, s30, 0x3eb38000
	s_addc_u32 s9, s31, 0
	s_mov_b32 s10, 0
	global_atomic_add v3, v2, v1, s[8:9] sc0
	s_waitcnt vmcnt(0)
	v_readfirstlane_b32 s0, v3
	s_add_u32 s0, s0, 1
	s_cmp_eq_u32 s0, s1
	s_cbranch_scc0 .Lgb8_pollg
	buffer_wbl2 sc1
	s_waitcnt vmcnt(0)
	s_add_u32 s8, s8, 0x1000
	s_addc_u32 s9, s9, 0
	global_atomic_add v3, v0, v1, s[8:9] sc0
	s_min_u32 s1, s99, 8
	s_mul_i32 s1, s1, 8
	s_waitcnt vmcnt(0)
	v_readfirstlane_b32 s0, v3
	s_add_u32 s0, s0, 1
	s_cmp_eq_u32 s0, s1
	s_cbranch_scc0 .Lgb8_pollt
	global_atomic_add v0, v1, s[8:9] offset:256
	s_branch .Lgb8_relg

; #define RUNPH(n) { run_phase(p, (n), smem); grid.sync(); }
; __global__ void __launch_bounds__(256, 2) mega(Params p) {
;   extern __shared__ __attribute__((aligned(16))) char smem[];
;   cg::grid_group grid = cg::this_grid();
;   RUNPH(0) RUNPH(1) RUNPH(2) RUNPH(3) RUNPH(4) RUNPH(5) RUNPH(6) RUNPH(7) RUNPH(8)
;   RUNPH(18) RUNPH(19) RUNPH(9)
;   RUNPH(10) RUNPH(11) RUNPH(12) RUNPH(13) RUNPH(14) RUNPH(15) RUNPH(16)
.LBB0_466:
	s_or_b64 exec, exec, s[6:7]
	s_waitcnt vmcnt(0)
	s_barrier
	s_mov_b64 s[6:7], exec
	v_readlane_b32 s0, v225, 14
	v_readlane_b32 s1, v225, 15
	s_and_b64 s[0:1], s[6:7], s[0:1]
	s_mov_b64 exec, s[0:1]
	s_cbranch_execz .LBB0_476
	s_cmp_eq_u32 s100, 1
	s_cbranch_scc1 .Lgb9_nowb
	buffer_wbl2 sc1
	s_waitcnt vmcnt(0)
.Lgb9_nowb:
	s_and_b32 s0, s98, 7
	s_sub_u32 s1, s99, s0
	s_add_u32 s1, s1, 7
	s_lshr_b32 s1, s1, 3
	s_mul_i32 s1, s1, 9
	s_lshl_b32 s0, s0, 8
	v_mov_b32_e32 v2, s0
	v_mov_b32_e32 v0, 0
	v_mov_b32_e32 v1, 1
	s_add_u32 s8, s30, 0x3eb38000
	s_addc_u32 s9, s31, 0
	s_mov_b32 s12, 0
	global_atomic_add v3, v2, v1, s[8:9] sc0
	s_waitcnt vmcnt(0)
	v_readfirstlane_b32 s0, v3
	s_add_u32 s0, s0, 1
	s_cmp_eq_u32 s0, s1
	s_cbranch_scc0 .Lgb9_pollg
	buffer_wbl2 sc1
	s_waitcnt vmcnt(0)
	s_add_u32 s8, s8, 0x1000
	s_addc_u32 s9, s9, 0
	global_atomic_add v3, v0, v1, s[8:9] sc0
	s_min_u32 s1, s99, 8
	s_mul_i32 s1, s1, 9
	s_waitcnt vmcnt(0)
	v_readfirstlane_b32 s0, v3
	s_add_u32 s0, s0, 1
	s_cmp_eq_u32 s0, s1
	s_cbranch_scc0 .Lgb9_pollt
	global_atomic_add v0, v1, s[8:9] offset:256
	s_branch .Lgb9_relg

; #define RUNPH(n) { run_phase(p, (n), smem); grid.sync(); }
; __global__ void __launch_bounds__(256, 2) mega(Params p) {
;   extern __shared__ __attribute__((aligned(16))) char smem[];
;   cg::grid_group grid = cg::this_grid();
;   RUNPH(0) RUNPH(1) RUNPH(2) RUNPH(3) RUNPH(4) RUNPH(5) RUNPH(6) RUNPH(7) RUNPH(8)
;   RUNPH(18) RUNPH(19) RUNPH(9)
;   RUNPH(10) RUNPH(11) RUNPH(12) RUNPH(13) RUNPH(14) RUNPH(15) RUNPH(16)
.Lgb10_nowb:
	s_and_b32 s0, s98, 7
	s_sub_u32 s1, s99, s0
	s_add_u32 s1, s1, 7
	s_lshr_b32 s1, s1, 3
	s_mul_i32 s1, s1, 10
	s_lshl_b32 s0, s0, 8
	v_mov_b32_e32 v2, s0
	v_mov_b32_e32 v0, 0
	v_mov_b32_e32 v1, 1
	s_add_u32 s14, s30, 0x3eb38000
	s_addc_u32 s15, s31, 0
	s_mov_b32 s16, 0
	global_atomic_add v3, v2, v1, s[14:15] sc0
	s_waitcnt vmcnt(0)
	v_readfirstlane_b32 s0, v3
	s_add_u32 s0, s0, 1
	s_cmp_eq_u32 s0, s1
	s_cbranch_scc0 .Lgb10_pollg
	buffer_wbl2 sc1
	s_waitcnt vmcnt(0)
	s_add_u32 s14, s14, 0x1000
	s_addc_u32 s15, s15, 0
	global_atomic_add v3, v0, v1, s[14:15] sc0
	s_min_u32 s1, s99, 8
	s_mul_i32 s1, s1, 10
	s_waitcnt vmcnt(0)
	v_readfirstlane_b32 s0, v3
	s_add_u32 s0, s0, 1
	s_cmp_eq_u32 s0, s1
	s_cbranch_scc0 .Lgb10_pollt
	global_atomic_add v0, v1, s[14:15] offset:256
	s_branch .Lgb10_relg

; #define RUNPH(n) { run_phase(p, (n), smem); grid.sync(); }
; __global__ void __launch_bounds__(256, 2) mega(Params p) {
;   extern __shared__ __attribute__((aligned(16))) char smem[];
;   cg::grid_group grid = cg::this_grid();
;   RUNPH(0) RUNPH(1) RUNPH(2) RUNPH(3) RUNPH(4) RUNPH(5) RUNPH(6) RUNPH(7) RUNPH(8)
;   RUNPH(18) RUNPH(19) RUNPH(9)
;   RUNPH(10) RUNPH(11) RUNPH(12) RUNPH(13) RUNPH(14) RUNPH(15) RUNPH(16)
.LBB0_1481:
	s_waitcnt vmcnt(0)
	s_barrier
	s_mov_b64 s[6:7], exec
	v_readlane_b32 s0, v225, 14
	v_readlane_b32 s1, v225, 15
	v_readlane_b32 s74, v225, 4
	s_and_b64 s[0:1], s[6:7], s[0:1]
	v_readlane_b32 s75, v225, 5
	v_readlane_b32 s92, v225, 16
	s_mov_b64 exec, s[0:1]
	s_cbranch_execz .LBB0_1491
	s_cmp_eq_u32 s100, 1
	s_cbranch_scc1 .Lgb11_nowb
	buffer_wbl2 sc1
	s_waitcnt vmcnt(0)
.Lgb11_nowb:
	s_and_b32 s0, s98, 7
	s_sub_u32 s1, s99, s0
	s_add_u32 s1, s1, 7
	s_lshr_b32 s1, s1, 3
	s_mul_i32 s1, s1, 11
	s_lshl_b32 s0, s0, 8
	v_mov_b32_e32 v2, s0
	v_mov_b32_e32 v0, 0
	v_mov_b32_e32 v1, 1
	s_add_u32 s8, s30, 0x3eb38000
	s_addc_u32 s9, s31, 0
	s_mov_b32 s12, 0
	global_atomic_add v3, v2, v1, s[8:9] sc0
	s_waitcnt vmcnt(0)
	v_readfirstlane_b32 s0, v3
	s_add_u32 s0, s0, 1
	s_cmp_eq_u32 s0, s1
	s_cbranch_scc0 .Lgb11_pollg
	buffer_wbl2 sc1
	s_waitcnt vmcnt(0)
	s_add_u32 s8, s8, 0x1000
	s_addc_u32 s9, s9, 0
	global_atomic_add v3, v0, v1, s[8:9] sc0
	s_min_u32 s1, s99, 8
	s_mul_i32 s1, s1, 11
	s_waitcnt vmcnt(0)
	v_readfirstlane_b32 s0, v3
	s_add_u32 s0, s0, 1
	s_cmp_eq_u32 s0, s1
	s_cbranch_scc0 .Lgb11_pollt
	global_atomic_add v0, v1, s[8:9] offset:256
	s_branch .Lgb11_relg

; #define RUNPH(n) { run_phase(p, (n), smem); grid.sync(); }
; __global__ void __launch_bounds__(256, 2) mega(Params p) {
;   extern __shared__ __attribute__((aligned(16))) char smem[];
;   cg::grid_group grid = cg::this_grid();
;   RUNPH(0) RUNPH(1) RUNPH(2) RUNPH(3) RUNPH(4) RUNPH(5) RUNPH(6) RUNPH(7) RUNPH(8)
;   RUNPH(18) RUNPH(19) RUNPH(9)
;   RUNPH(10) RUNPH(11) RUNPH(12) RUNPH(13) RUNPH(14) RUNPH(15) RUNPH(16)
.LBB0_1498:
	s_waitcnt vmcnt(0)
	s_barrier
	s_mov_b64 s[6:7], exec
	v_readlane_b32 s0, v225, 14
	v_readlane_b32 s1, v225, 15
	s_and_b64 s[0:1], s[6:7], s[0:1]
	v_readlane_b32 s96, v225, 2
	v_readlane_b32 s97, v225, 3
	s_mov_b64 exec, s[0:1]
	s_cbranch_execz .LBB0_1508
	s_cmp_eq_u32 s100, 1
	s_cbranch_scc1 .Lgb12_nowb
	buffer_wbl2 sc1
	s_waitcnt vmcnt(0)
.Lgb12_nowb:
	s_and_b32 s0, s98, 7
	s_sub_u32 s1, s99, s0
	s_add_u32 s1, s1, 7
	s_lshr_b32 s1, s1, 3
	s_mul_i32 s1, s1, 12
	s_lshl_b32 s0, s0, 8
	v_mov_b32_e32 v2, s0
	v_mov_b32_e32 v0, 0
	v_mov_b32_e32 v1, 1
	s_add_u32 s8, s30, 0x3eb38000
	s_addc_u32 s9, s31, 0
	s_mov_b32 s12, 0
	global_atomic_add v3, v2, v1, s[8:9] sc0
	s_waitcnt vmcnt(0)
	v_readfirstlane_b32 s0, v3
	s_add_u32 s0, s0, 1
	s_cmp_eq_u32 s0, s1
	s_cbranch_scc0 .Lgb12_pollg
	buffer_wbl2 sc1
	s_waitcnt vmcnt(0)
	s_add_u32 s8, s8, 0x1000
	s_addc_u32 s9, s9, 0
	global_atomic_add v3, v0, v1, s[8:9] sc0
	s_min_u32 s1, s99, 8
	s_mul_i32 s1, s1, 12
	s_waitcnt vmcnt(0)
	v_readfirstlane_b32 s0, v3
	s_add_u32 s0, s0, 1
	s_cmp_eq_u32 s0, s1
	s_cbranch_scc0 .Lgb12_pollt
	global_atomic_add v0, v1, s[8:9] offset:256
	s_branch .Lgb12_relg

; #define RUNPH(n) { run_phase(p, (n), smem); grid.sync(); }
; __global__ void __launch_bounds__(256, 2) mega(Params p) {
;   extern __shared__ __attribute__((aligned(16))) char smem[];
;   cg::grid_group grid = cg::this_grid();
;   RUNPH(0) RUNPH(1) RUNPH(2) RUNPH(3) RUNPH(4) RUNPH(5) RUNPH(6) RUNPH(7) RUNPH(8)
;   RUNPH(18) RUNPH(19) RUNPH(9)
;   RUNPH(10) RUNPH(11) RUNPH(12) RUNPH(13) RUNPH(14) RUNPH(15) RUNPH(16)
.Lgb13_nowb:
	s_and_b32 s0, s98, 7
	s_sub_u32 s1, s99, s0
	s_add_u32 s1, s1, 7
	s_lshr_b32 s1, s1, 3
	s_mul_i32 s1, s1, 13
	s_lshl_b32 s0, s0, 8
	v_mov_b32_e32 v2, s0
	v_mov_b32_e32 v0, 0
	v_mov_b32_e32 v1, 1
	s_add_u32 s8, s30, 0x3eb38000
	s_addc_u32 s9, s31, 0
	s_mov_b32 s12, 0
	global_atomic_add v3, v2, v1, s[8:9] sc0
	s_waitcnt vmcnt(0)
	v_readfirstlane_b32 s0, v3
	s_add_u32 s0, s0, 1
	s_cmp_eq_u32 s0, s1
	s_cbranch_scc0 .Lgb13_pollg
	buffer_wbl2 sc1
	s_waitcnt vmcnt(0)
	s_add_u32 s8, s8, 0x1000
	s_addc_u32 s9, s9, 0
	global_atomic_add v3, v0, v1, s[8:9] sc0
	s_min_u32 s1, s99, 8
	s_mul_i32 s1, s1, 13
	s_waitcnt vmcnt(0)
	v_readfirstlane_b32 s0, v3
	s_add_u32 s0, s0, 1
	s_cmp_eq_u32 s0, s1
	s_cbranch_scc0 .Lgb13_pollt
	global_atomic_add v0, v1, s[8:9] offset:256
	s_branch .Lgb13_relg

; #define RUNPH(n) { run_phase(p, (n), smem); grid.sync(); }
; __global__ void __launch_bounds__(256, 2) mega(Params p) {
;   extern __shared__ __attribute__((aligned(16))) char smem[];
;   cg::grid_group grid = cg::this_grid();
;   RUNPH(0) RUNPH(1) RUNPH(2) RUNPH(3) RUNPH(4) RUNPH(5) RUNPH(6) RUNPH(7) RUNPH(8)
;   RUNPH(18) RUNPH(19) RUNPH(9)
;   RUNPH(10) RUNPH(11) RUNPH(12) RUNPH(13) RUNPH(14) RUNPH(15) RUNPH(16)
.Lgb14_nowb:
	s_and_b32 s0, s98, 7
	s_sub_u32 s1, s99, s0
	s_add_u32 s1, s1, 7
	s_lshr_b32 s1, s1, 3
	s_mul_i32 s1, s1, 14
	s_lshl_b32 s0, s0, 8
	v_mov_b32_e32 v2, s0
	v_mov_b32_e32 v0, 0
	v_mov_b32_e32 v1, 1
	s_add_u32 s8, s30, 0x3eb38000
	s_addc_u32 s9, s31, 0
	s_mov_b32 s12, 0
	global_atomic_add v3, v2, v1, s[8:9] sc0
	s_waitcnt vmcnt(0)
	v_readfirstlane_b32 s0, v3
	s_add_u32 s0, s0, 1
	s_cmp_eq_u32 s0, s1
	s_cbranch_scc0 .Lgb14_pollg
	buffer_wbl2 sc1
	s_waitcnt vmcnt(0)
	s_add_u32 s8, s8, 0x1000
	s_addc_u32 s9, s9, 0
	global_atomic_add v3, v0, v1, s[8:9] sc0
	s_min_u32 s1, s99, 8
	s_mul_i32 s1, s1, 14
	s_waitcnt vmcnt(0)
	v_readfirstlane_b32 s0, v3
	s_add_u32 s0, s0, 1
	s_cmp_eq_u32 s0, s1
	s_cbranch_scc0 .Lgb14_pollt
	global_atomic_add v0, v1, s[8:9] offset:256
	s_branch .Lgb14_relg

; #define RUNPH(n) { run_phase(p, (n), smem); grid.sync(); }
; __global__ void __launch_bounds__(256, 2) mega(Params p) {
;   extern __shared__ __attribute__((aligned(16))) char smem[];
;   cg::grid_group grid = cg::this_grid();
;   RUNPH(0) RUNPH(1) RUNPH(2) RUNPH(3) RUNPH(4) RUNPH(5) RUNPH(6) RUNPH(7) RUNPH(8)
;   RUNPH(18) RUNPH(19) RUNPH(9)
;   RUNPH(10) RUNPH(11) RUNPH(12) RUNPH(13) RUNPH(14) RUNPH(15) RUNPH(16)
.Lgb15_nowb:
	s_and_b32 s0, s98, 7
	s_sub_u32 s1, s99, s0
	s_add_u32 s1, s1, 7
	s_lshr_b32 s1, s1, 3
	s_mul_i32 s1, s1, 15
	s_lshl_b32 s0, s0, 8
	v_mov_b32_e32 v2, s0
	v_mov_b32_e32 v0, 0
	v_mov_b32_e32 v1, 1
	s_add_u32 s8, s30, 0x3eb38000
	s_addc_u32 s9, s31, 0
	s_mov_b32 s12, 0
	global_atomic_add v3, v2, v1, s[8:9] sc0
	s_waitcnt vmcnt(0)
	v_readfirstlane_b32 s0, v3
	s_add_u32 s0, s0, 1
	s_cmp_eq_u32 s0, s1
	s_cbranch_scc0 .Lgb15_pollg
	buffer_wbl2 sc1
	s_waitcnt vmcnt(0)
	s_add_u32 s8, s8, 0x1000
	s_addc_u32 s9, s9, 0
	global_atomic_add v3, v0, v1, s[8:9] sc0
	s_min_u32 s1, s99, 8
	s_mul_i32 s1, s1, 15
	s_waitcnt vmcnt(0)
	v_readfirstlane_b32 s0, v3
	s_add_u32 s0, s0, 1
	s_cmp_eq_u32 s0, s1
	s_cbranch_scc0 .Lgb15_pollt
	global_atomic_add v0, v1, s[8:9] offset:256
	s_branch .Lgb15_relg

; #define RUNPH(n) { run_phase(p, (n), smem); grid.sync(); }
; __global__ void __launch_bounds__(256, 2) mega(Params p) {
;   extern __shared__ __attribute__((aligned(16))) char smem[];
;   cg::grid_group grid = cg::this_grid();
;   RUNPH(0) RUNPH(1) RUNPH(2) RUNPH(3) RUNPH(4) RUNPH(5) RUNPH(6) RUNPH(7) RUNPH(8)
;   RUNPH(18) RUNPH(19) RUNPH(9)
;   RUNPH(10) RUNPH(11) RUNPH(12) RUNPH(13) RUNPH(14) RUNPH(15) RUNPH(16)
.Lgb16_nowb:
	s_and_b32 s0, s98, 7
	s_sub_u32 s1, s99, s0
	s_add_u32 s1, s1, 7
	s_lshr_b32 s1, s1, 3
	s_mul_i32 s1, s1, 16
	s_lshl_b32 s0, s0, 8
	v_mov_b32_e32 v2, s0
	v_mov_b32_e32 v0, 0
	v_mov_b32_e32 v1, 1
	s_add_u32 s8, s30, 0x3eb38000
	s_addc_u32 s9, s31, 0
	s_mov_b32 s12, 0
	global_atomic_add v3, v2, v1, s[8:9] sc0
	s_waitcnt vmcnt(0)
	v_readfirstlane_b32 s0, v3
	s_add_u32 s0, s0, 1
	s_cmp_eq_u32 s0, s1
	s_cbranch_scc0 .Lgb16_pollg
	buffer_wbl2 sc1
	s_waitcnt vmcnt(0)
	s_add_u32 s8, s8, 0x1000
	s_addc_u32 s9, s9, 0
	global_atomic_add v3, v0, v1, s[8:9] sc0
	s_min_u32 s1, s99, 8
	s_mul_i32 s1, s1, 16
	s_waitcnt vmcnt(0)
	v_readfirstlane_b32 s0, v3
	s_add_u32 s0, s0, 1
	s_cmp_eq_u32 s0, s1
	s_cbranch_scc0 .Lgb16_pollt
	global_atomic_add v0, v1, s[8:9] offset:256
	s_branch .Lgb16_relg

; #define RUNPH(n) { run_phase(p, (n), smem); grid.sync(); }
; __global__ void __launch_bounds__(256, 2) mega(Params p) {
;   extern __shared__ __attribute__((aligned(16))) char smem[];
;   cg::grid_group grid = cg::this_grid();
;   RUNPH(0) RUNPH(1) RUNPH(2) RUNPH(3) RUNPH(4) RUNPH(5) RUNPH(6) RUNPH(7) RUNPH(8)
;   RUNPH(18) RUNPH(19) RUNPH(9)
;   RUNPH(10) RUNPH(11) RUNPH(12) RUNPH(13) RUNPH(14) RUNPH(15) RUNPH(16)
.Lgb17_nowb:
	s_and_b32 s0, s98, 7
	s_sub_u32 s1, s99, s0
	s_add_u32 s1, s1, 7
	s_lshr_b32 s1, s1, 3
	s_mul_i32 s1, s1, 17
	s_lshl_b32 s0, s0, 8
	v_mov_b32_e32 v2, s0
	v_mov_b32_e32 v0, 0
	v_mov_b32_e32 v1, 1
	s_add_u32 s8, s30, 0x3eb38000
	s_addc_u32 s9, s31, 0
	s_mov_b32 s12, 0
	global_atomic_add v3, v2, v1, s[8:9] sc0
	s_waitcnt vmcnt(0)
	v_readfirstlane_b32 s0, v3
	s_add_u32 s0, s0, 1
	s_cmp_eq_u32 s0, s1
	s_cbranch_scc0 .Lgb17_pollg
	buffer_wbl2 sc1
	s_waitcnt vmcnt(0)
	s_add_u32 s8, s8, 0x1000
	s_addc_u32 s9, s9, 0
	global_atomic_add v3, v0, v1, s[8:9] sc0
	s_min_u32 s1, s99, 8
	s_mul_i32 s1, s1, 17
	s_waitcnt vmcnt(0)
	v_readfirstlane_b32 s0, v3
	s_add_u32 s0, s0, 1
	s_cmp_eq_u32 s0, s1
	s_cbranch_scc0 .Lgb17_pollt
	global_atomic_add v0, v1, s[8:9] offset:256
	s_branch .Lgb17_relg

; #define RUNPH(n) { run_phase(p, (n), smem); grid.sync(); }
; __global__ void __launch_bounds__(256, 2) mega(Params p) {
;   extern __shared__ __attribute__((aligned(16))) char smem[];
;   cg::grid_group grid = cg::this_grid();
;   RUNPH(0) RUNPH(1) RUNPH(2) RUNPH(3) RUNPH(4) RUNPH(5) RUNPH(6) RUNPH(7) RUNPH(8)
;   RUNPH(18) RUNPH(19) RUNPH(9)
;   RUNPH(10) RUNPH(11) RUNPH(12) RUNPH(13) RUNPH(14) RUNPH(15) RUNPH(16)
.Lgb18_nowb:
	s_and_b32 s0, s98, 7
	s_sub_u32 s1, s99, s0
	s_add_u32 s1, s1, 7
	s_lshr_b32 s1, s1, 3
	s_mul_i32 s1, s1, 18
	s_lshl_b32 s0, s0, 8
	v_mov_b32_e32 v2, s0
	v_mov_b32_e32 v0, 0
	v_mov_b32_e32 v1, 1
	s_add_u32 s2, s30, 0x3eb38000
	s_addc_u32 s3, s31, 0
	s_mov_b32 s8, 0
	global_atomic_add v3, v2, v1, s[2:3] sc0
	s_waitcnt vmcnt(0)
	v_readfirstlane_b32 s0, v3
	s_add_u32 s0, s0, 1
	s_cmp_eq_u32 s0, s1
	s_cbranch_scc0 .Lgb18_pollg
	buffer_wbl2 sc1
	s_waitcnt vmcnt(0)
	s_add_u32 s2, s2, 0x1000
	s_addc_u32 s3, s3, 0
	global_atomic_add v3, v0, v1, s[2:3] sc0
	s_min_u32 s1, s99, 8
	s_mul_i32 s1, s1, 18
	s_waitcnt vmcnt(0)
	v_readfirstlane_b32 s0, v3
	s_add_u32 s0, s0, 1
	s_cmp_eq_u32 s0, s1
	s_cbranch_scc0 .Lgb18_pollt
	global_atomic_add v0, v1, s[2:3] offset:256
	s_branch .Lgb18_relg

; __global__ void __launch_bounds__(256, 2) mega(Params p) {
;   extern __shared__ __attribute__((aligned(16))) char smem[];
;   cg::grid_group grid = cg::this_grid();
	.amdhsa_kernel _Z4mega6Params
		.amdhsa_group_segment_fixed_size 0
		.amdhsa_private_segment_fixed_size 0
		.amdhsa_kernarg_size 496
		.amdhsa_user_sgpr_count 2
		.amdhsa_user_sgpr_dispatch_ptr 0
		.amdhsa_user_sgpr_queue_ptr 0
		.amdhsa_user_sgpr_kernarg_segment_ptr 1
		.amdhsa_user_sgpr_dispatch_id 0
		.amdhsa_user_sgpr_kernarg_preload_length 0
		.amdhsa_user_sgpr_kernarg_preload_offset 0
		.amdhsa_user_sgpr_private_segment_size 0
		.amdhsa_uses_dynamic_stack 0
		.amdhsa_enable_private_segment 0
		.amdhsa_system_sgpr_workgroup_id_x 1
		.amdhsa_system_sgpr_workgroup_id_y 0
		.amdhsa_system_sgpr_workgroup_id_z 0
		.amdhsa_system_sgpr_workgroup_info 0
		.amdhsa_system_vgpr_workitem_id 2
		.amdhsa_next_free_vgpr 256
		.amdhsa_next_free_sgpr 102
		.amdhsa_accum_offset 256
		.amdhsa_reserve_vcc 1
		.amdhsa_float_round_mode_32 0
		.amdhsa_float_round_mode_16_64 0
		.amdhsa_float_denorm_mode_32 3
		.amdhsa_float_denorm_mode_16_64 3
		.amdhsa_dx10_clamp 1
		.amdhsa_ieee_mode 1
		.amdhsa_fp16_overflow 0
		.amdhsa_tg_split 0
		.amdhsa_exception_fp_ieee_invalid_op 0
		.amdhsa_exception_fp_denorm_src 0
		.amdhsa_exception_fp_ieee_div_zero 0
		.amdhsa_exception_fp_ieee_overflow 0
		.amdhsa_exception_fp_ieee_underflow 0
		.amdhsa_exception_fp_ieee_inexact 0
		.amdhsa_exception_int_div_zero 0
	.end_amdhsa_kernel

; __global__ void __launch_bounds__(256, 2) mega(Params p) {
;   extern __shared__ __attribute__((aligned(16))) char smem[];
;   cg::grid_group grid = cg::this_grid();
amdhsa.kernels:
  - .agpr_count:     0
    .args:
      - .offset:         0
        .size:           240
        .value_kind:     by_value
      - .offset:         240
        .size:           4
        .value_kind:     hidden_block_count_x
      - .offset:         244
        .size:           4
        .value_kind:     hidden_block_count_y
      - .offset:         248
        .size:           4
        .value_kind:     hidden_block_count_z
      - .offset:         252
        .size:           2
        .value_kind:     hidden_group_size_x
      - .offset:         254
        .size:           2
        .value_kind:     hidden_group_size_y
      - .offset:         256
        .size:           2
        .value_kind:     hidden_group_size_z
      - .offset:         258
        .size:           2
        .value_kind:     hidden_remainder_x
      - .offset:         260
        .size:           2
        .value_kind:     hidden_remainder_y
      - .offset:         262
        .size:           2
        .value_kind:     hidden_remainder_z
      - .offset:         280
        .size:           8
        .value_kind:     hidden_global_offset_x
      - .offset:         288
        .size:           8
        .value_kind:     hidden_global_offset_y
      - .offset:         296
        .size:           8
        .value_kind:     hidden_global_offset_z
      - .offset:         304
        .size:           2
        .value_kind:     hidden_grid_dims
      - .offset:         328
        .size:           8
        .value_kind:     hidden_multigrid_sync_arg
      - .offset:         360
        .size:           4
        .value_kind:     hidden_dynamic_lds_size
    .group_segment_fixed_size: 0
    .kernarg_segment_align: 8
    .kernarg_segment_size: 496
    .language:       OpenCL C
    .language_version:
      - 2
      - 0
    .max_flat_workgroup_size: 256
    .name:           _Z4mega6Params
    .private_segment_fixed_size: 0
    .sgpr_count:     108
    .sgpr_spill_count: 57
    .symbol:         _Z4mega6Params.kd
    .uniform_work_group_size: 1
    .uses_dynamic_stack: false
    .vgpr_count:     256
    .vgpr_spill_count: 0
    .wavefront_size: 64
